# stack on PV-MFMA hoist: aux LDS-DMA dedupe + dead m0 save/restore removed, MLA negm copies removed (SrcC direct), cross-half row max only in the rare rescale path
# speedup vs baseline: 1.0208x; 1.0083x over previous
; template <int TYPE> __device__ __forceinline__ void attn_unit(LAS unsigned char* lds, const AttnUnit& U) {
;     ...
;         float mt; A_ROWMAX(s0, s1, mt);
;         bool resc = false;
;         if (__any(mt > THR)) {
;             const float dl = fmaxf(mt, 0.f); mref += dl;
; #pragma unroll
;             for (int r = 0; r < 16; ++r) { s0[r] -= dl; s1[r] -= dl; if (TYPE == 0) negm[r] = -mref; }
;             if (hi == 0) wsf[r32] = __builtin_amdgcn_exp2f(-dl);
.LBB0_678:
	s_lshl_b32 s6, s77, 13
	s_add_i32 s6, s6, 0xc000
	v_add_u32_e32 v0, s6, v174
	v_add_u32_e32 v14, s6, v173
	ds_read_b64_tr_b16 v[2:3], v0
	ds_read_b64_tr_b16 v[4:5], v0 offset:1024
	ds_read_b64_tr_b16 v[6:7], v14
	ds_read_b64_tr_b16 v[8:9], v14 offset:1024
	s_mov_b32 s77, s76
	s_mov_b32 s78, s76
	s_mov_b32 s79, s76
	v_mov_b64_e32 v[10:11], s[76:77]
	v_mov_b64_e32 v[12:13], s[78:79]
	ds_read_b64_tr_b16 v[178:179], v0 offset:2048
	ds_read_b64_tr_b16 v[180:181], v0 offset:3072
	ds_read_b64_tr_b16 v[192:193], v14 offset:2048
	ds_read_b64_tr_b16 v[194:195], v14 offset:3072
	v_mfma_f32_32x32x16_bf16 v[48:63], v[148:151], v[10:13], v[48:63]
	v_max_f32_e32 v236, v97, v97
	v_max_f32_e32 v237, v96, v96
	v_max_f32_e32 v236, v237, v236
	v_max3_f32 v237, v98, v99, v113
	v_max3_f32 v236, v236, v112, v114
	v_max3_f32 v236, v236, v115, v100
	v_max3_f32 v237, v237, v102, v103
	s_waitcnt lgkmcnt(6)
	v_mfma_f32_32x32x16_bf16 v[32:47], v[148:151], v[2:5], v[32:47]
	v_max3_f32 v236, v236, v101, v116
	v_max3_f32 v237, v237, v118, v119
	v_max3_f32 v236, v236, v117, v104
	v_max3_f32 v237, v237, v106, v107
	v_max3_f32 v236, v236, v105, v120
	v_max3_f32 v237, v237, v122, v123
	s_waitcnt lgkmcnt(4)
	v_mfma_f32_32x32x16_bf16 v[16:31], v[148:151], v[6:9], v[16:31]
	v_max3_f32 v236, v236, v121, v108
	v_max3_f32 v237, v237, v110, v111
	v_max3_f32 v236, v236, v109, v124
	v_max3_f32 v237, v237, v126, v127
	v_max3_f32 v236, v236, v125, v237
	v_cmp_lt_f32_e32 vcc, s90, v236
	s_cmp_lg_u64 vcc, 0
	s_cselect_b64 s[72:73], -1, 0
	s_cbranch_vccz .LBB0_682
	v_mov_b32_e32 v237, v236
	s_nop 1
	v_permlane32_swap_b32_e32 v236, v237
	v_max_f32_e32 v237, v237, v237
	v_max_f32_e32 v236, v236, v236
	v_max_f32_e32 v236, v236, v237
	v_max_f32_e32 v236, v236, v236
	v_max_f32_e32 v236, 0, v236
	s_and_saveexec_b64 s[78:79], s[4:5]
	v_exp_f32_e64 v237, -v236
	ds_write_b32 v176, v237
	s_or_b64 exec, exec, s[78:79]
	v_sub_f32_e32 v111, v111, v236
	v_sub_f32_e32 v110, v110, v236
	v_sub_f32_e32 v109, v109, v236
	v_sub_f32_e32 v108, v108, v236
	v_sub_f32_e32 v107, v107, v236
	v_sub_f32_e32 v106, v106, v236
	v_sub_f32_e32 v105, v105, v236
	v_sub_f32_e32 v104, v104, v236
	v_sub_f32_e32 v103, v103, v236
	v_sub_f32_e32 v102, v102, v236
	v_sub_f32_e32 v101, v101, v236
	v_sub_f32_e32 v100, v100, v236
	v_sub_f32_e32 v99, v99, v236
	v_sub_f32_e32 v98, v98, v236
	v_sub_f32_e32 v97, v97, v236
	v_sub_f32_e32 v96, v96, v236
	v_sub_f32_e32 v127, v127, v236
	v_sub_f32_e32 v126, v126, v236
	v_sub_f32_e32 v125, v125, v236
	v_sub_f32_e32 v124, v124, v236
	v_sub_f32_e32 v123, v123, v236
	v_sub_f32_e32 v122, v122, v236
	v_sub_f32_e32 v121, v121, v236
	v_sub_f32_e32 v120, v120, v236
	v_sub_f32_e32 v119, v119, v236
	v_sub_f32_e32 v118, v118, v236
	v_sub_f32_e32 v117, v117, v236
	v_sub_f32_e32 v116, v116, v236
	v_sub_f32_e32 v115, v115, v236
	v_sub_f32_e32 v114, v114, v236
	v_sub_f32_e32 v113, v113, v236
	v_sub_f32_e32 v112, v112, v236
	v_add_f32_e32 v160, v160, v236

.LBB0_748:
	s_add_i32 s72, s33, s93
	s_waitcnt lgkmcnt(1)
	v_mfma_f32_32x32x16_bf16 v[128:143], v[6:9], v[144:147], v[96:111]
	v_add_u32_e32 v0, s78, v204
	ds_read_b128 v[10:13], v0
	ds_read_b128 v[212:215], v0 offset:4096
	v_cvt_pk_bf16_f32 v172, v80, v81
	v_cvt_pk_bf16_f32 v173, v82, v83
	v_cvt_pk_bf16_f32 v174, v84, v85
	v_cvt_pk_bf16_f32 v175, v86, v87
	s_waitcnt lgkmcnt(2)
	v_mfma_f32_32x32x16_bf16 v[112:127], v[2:5], v[144:147], v[96:111]
	s_waitcnt lgkmcnt(1)
	v_mfma_f32_32x32x16_bf16 v[128:143], v[10:13], v[148:151], v[128:143]
	v_add_u32_e32 v0, s78, v205
	ds_read_b128 v[2:5], v0
	ds_read_b128 v[6:9], v0 offset:4096
	v_cvt_pk_bf16_f32 v176, v88, v89
	v_cvt_pk_bf16_f32 v177, v90, v91
	s_waitcnt lgkmcnt(2)
	v_mfma_f32_32x32x16_bf16 v[112:127], v[212:215], v[148:151], v[112:127]
	v_cvt_pk_bf16_f32 v178, v92, v93
	v_cvt_pk_bf16_f32 v179, v94, v95
	s_waitcnt lgkmcnt(1)
	v_mfma_f32_32x32x16_bf16 v[128:143], v[2:5], v[152:155], v[128:143]
	v_add_u32_e32 v0, s78, v206
	ds_read_b128 v[10:13], v0
	ds_read_b128 v[212:215], v0 offset:4096
	v_cvt_pk_bf16_f32 v180, v64, v65
	v_cvt_pk_bf16_f32 v181, v66, v67
	s_waitcnt lgkmcnt(2)
	v_mfma_f32_32x32x16_bf16 v[112:127], v[6:9], v[152:155], v[112:127]
	v_cvt_pk_bf16_f32 v182, v68, v69
	v_cvt_pk_bf16_f32 v183, v70, v71
	s_waitcnt lgkmcnt(1)
	v_mfma_f32_32x32x16_bf16 v[128:143], v[10:13], v[156:159], v[128:143]
	v_add_u32_e32 v0, s78, v207
	ds_read_b128 v[2:5], v0
	ds_read_b128 v[6:9], v0 offset:2048
	v_cvt_pk_bf16_f32 v168, v72, v73
	v_cvt_pk_bf16_f32 v169, v74, v75
	s_waitcnt lgkmcnt(2)
	v_mfma_f32_32x32x16_bf16 v[112:127], v[212:215], v[156:159], v[112:127]
	v_cvt_pk_bf16_f32 v170, v76, v77
	v_cvt_pk_bf16_f32 v171, v78, v79
	s_waitcnt lgkmcnt(1)
	v_mfma_f32_32x32x16_bf16 v[128:143], v[2:5], v[160:163], v[128:143]
	v_add_u32_e32 v0, s78, v208
	ds_read_b128 v[10:13], v0
	ds_read_b128 v[212:215], v0 offset:2048
	s_waitcnt lgkmcnt(2)
	v_mfma_f32_32x32x16_bf16 v[112:127], v[6:9], v[160:163], v[112:127]
	s_waitcnt lgkmcnt(1)
	v_mfma_f32_32x32x16_bf16 v[128:143], v[10:13], v[164:167], v[128:143]
	s_waitcnt lgkmcnt(0)
	v_mfma_f32_32x32x16_bf16 v[112:127], v[212:215], v[164:167], v[112:127]
	s_cmp_lg_u32 s72, 0
	s_cbranch_scc1 .LBB0_750
	v_readlane_b32 s40, v226, 40
	v_readlane_b32 s41, v226, 41
	s_nop 5
	v_cndmask_b32_e64 v143, v188, v143, s[6:7]
	v_cndmask_b32_e64 v142, v188, v142, s[10:11]
	v_cndmask_b32_e64 v141, v188, v141, s[12:13]
	v_cndmask_b32_e64 v140, v188, v140, s[14:15]
	v_cndmask_b32_e64 v139, v188, v139, s[16:17]
	v_cndmask_b32_e64 v138, v188, v138, s[18:19]
	v_cndmask_b32_e64 v137, v188, v137, s[20:21]
	v_cndmask_b32_e64 v136, v188, v136, s[22:23]
	v_cndmask_b32_e64 v135, v188, v135, s[24:25]
	v_cndmask_b32_e64 v134, v188, v134, s[26:27]
	v_cndmask_b32_e64 v133, v188, v133, s[28:29]
	v_cndmask_b32_e64 v132, v188, v132, s[30:31]
	v_cndmask_b32_e64 v131, v188, v131, s[34:35]
	v_cndmask_b32_e64 v130, v188, v130, s[36:37]
	v_cndmask_b32_e64 v129, v188, v129, s[38:39]
	v_cndmask_b32_e64 v128, v188, v128, s[40:41]
	v_cndmask_b32_e64 v127, v188, v127, s[8:9]
	v_cndmask_b32_e64 v126, v188, v126, s[42:43]
	v_cndmask_b32_e64 v125, v188, v125, s[44:45]
	v_cndmask_b32_e64 v124, v188, v124, s[46:47]
	v_cndmask_b32_e64 v123, v188, v123, s[48:49]
	v_cndmask_b32_e64 v122, v188, v122, s[50:51]
	v_cndmask_b32_e64 v121, v188, v121, s[52:53]
	v_cndmask_b32_e64 v120, v188, v120, s[54:55]
	v_cndmask_b32_e64 v119, v188, v119, s[56:57]
	v_cndmask_b32_e64 v118, v188, v118, s[58:59]
	v_cndmask_b32_e64 v117, v188, v117, s[60:61]
	v_cndmask_b32_e64 v116, v188, v116, s[62:63]
	v_cndmask_b32_e64 v115, v188, v115, s[64:65]
	v_cndmask_b32_e64 v114, v188, v114, s[66:67]
	v_cndmask_b32_e64 v113, v188, v113, s[68:69]
	v_cndmask_b32_e64 v112, v188, v112, s[70:71]
; template <int TYPE> __device__ __forceinline__ void attn_unit(LAS unsigned char* lds, const AttnUnit& U) {
;     ...
;         float mt; A_ROWMAX(s0, s1, mt);
;         bool resc = false;
;         if (__any(mt > THR)) {
;             const float dl = fmaxf(mt, 0.f); mref += dl;
; #pragma unroll
;             for (int r = 0; r < 16; ++r) { s0[r] -= dl; s1[r] -= dl; if (TYPE == 0) negm[r] = -mref; }
;             if (hi == 0) wsf[r32] = __builtin_amdgcn_exp2f(-dl);
.LBB0_750:
	s_lshl_b32 s77, s77, 13
	s_add_i32 s77, s77, 0xc000
	v_add_u32_e32 v0, s77, v200
	v_add_u32_e32 v14, s77, v201
	ds_read_b64_tr_b16 v[2:3], v0
	ds_read_b64_tr_b16 v[4:5], v0 offset:1024
	ds_read_b64_tr_b16 v[6:7], v14
	ds_read_b64_tr_b16 v[8:9], v14 offset:1024
	s_mov_b32 s77, s76
	s_mov_b32 s78, s76
	s_mov_b32 s79, s76
	v_mov_b64_e32 v[10:11], s[76:77]
	v_mov_b64_e32 v[12:13], s[78:79]
	ds_read_b64_tr_b16 v[212:213], v0 offset:2048
	ds_read_b64_tr_b16 v[214:215], v0 offset:3072
	ds_read_b64_tr_b16 v[216:217], v14 offset:2048
	ds_read_b64_tr_b16 v[218:219], v14 offset:3072
	v_mfma_f32_32x32x16_bf16 v[48:63], v[172:175], v[10:13], v[48:63]
	v_max_f32_e32 v236, v129, v129
	v_max_f32_e32 v237, v128, v128
	v_max_f32_e32 v236, v237, v236
	v_max3_f32 v237, v130, v131, v113
	v_max3_f32 v236, v236, v112, v114
	v_max3_f32 v236, v236, v115, v132
	v_max3_f32 v237, v237, v134, v135
	s_waitcnt lgkmcnt(6)
	v_mfma_f32_32x32x16_bf16 v[32:47], v[172:175], v[2:5], v[32:47]
	v_max3_f32 v236, v236, v133, v116
	v_max3_f32 v237, v237, v118, v119
	v_max3_f32 v236, v236, v117, v136
	v_max3_f32 v237, v237, v138, v139
	v_max3_f32 v236, v236, v137, v120
	v_max3_f32 v237, v237, v122, v123
	s_waitcnt lgkmcnt(4)
	v_mfma_f32_32x32x16_bf16 v[16:31], v[172:175], v[6:9], v[16:31]
	v_max3_f32 v236, v236, v121, v140
	v_max3_f32 v237, v237, v142, v143
	v_max3_f32 v236, v236, v141, v124
	v_max3_f32 v237, v237, v126, v127
	v_max3_f32 v236, v236, v125, v237
	v_cmp_lt_f32_e32 vcc, s90, v236
	s_cmp_lg_u64 vcc, 0
	s_cselect_b64 s[72:73], -1, 0
	s_cbranch_vccz .LBB0_754
	v_mov_b32_e32 v237, v236
	s_nop 1
	v_permlane32_swap_b32_e32 v236, v237
	v_max_f32_e32 v237, v237, v237
	v_max_f32_e32 v236, v236, v236
	v_max_f32_e32 v236, v236, v237
	v_max_f32_e32 v236, v236, v236
	v_max_f32_e32 v236, 0, v236
	s_and_saveexec_b64 s[78:79], s[4:5]
	v_exp_f32_e64 v237, -v236
	ds_write_b32 v209, v237
	s_or_b64 exec, exec, s[78:79]
	v_add_f32_e32 v202, v202, v236
	v_xor_b32_e32 v96, 0x80000000, v202
	v_sub_f32_e32 v143, v143, v236
	v_sub_f32_e32 v142, v142, v236
	v_sub_f32_e32 v141, v141, v236
	v_sub_f32_e32 v140, v140, v236
	v_sub_f32_e32 v139, v139, v236
	v_sub_f32_e32 v138, v138, v236
	v_sub_f32_e32 v137, v137, v236
	v_sub_f32_e32 v136, v136, v236
	v_sub_f32_e32 v135, v135, v236
	v_sub_f32_e32 v134, v134, v236
	v_sub_f32_e32 v133, v133, v236
	v_sub_f32_e32 v132, v132, v236
	v_sub_f32_e32 v131, v131, v236
	v_sub_f32_e32 v130, v130, v236
	v_sub_f32_e32 v129, v129, v236
	v_sub_f32_e32 v128, v128, v236
	v_sub_f32_e32 v127, v127, v236
	v_sub_f32_e32 v126, v126, v236
	v_sub_f32_e32 v125, v125, v236
	v_sub_f32_e32 v124, v124, v236
	v_sub_f32_e32 v123, v123, v236
	v_sub_f32_e32 v122, v122, v236
	v_sub_f32_e32 v121, v121, v236
	v_sub_f32_e32 v120, v120, v236
	v_sub_f32_e32 v119, v119, v236
	v_sub_f32_e32 v118, v118, v236
	v_sub_f32_e32 v117, v117, v236
	v_sub_f32_e32 v116, v116, v236
	v_sub_f32_e32 v115, v115, v236
	v_sub_f32_e32 v114, v114, v236
	v_sub_f32_e32 v113, v113, v236
	v_sub_f32_e32 v112, v112, v236
	v_mov_b32_e32 v97, v96
	v_mov_b32_e32 v98, v96
	v_mov_b32_e32 v99, v96
	v_mov_b32_e32 v100, v96
	v_mov_b32_e32 v101, v96
	v_mov_b32_e32 v102, v96
	v_mov_b32_e32 v103, v96
	v_mov_b32_e32 v104, v96
	v_mov_b32_e32 v105, v96
	v_mov_b32_e32 v106, v96
	v_mov_b32_e32 v107, v96
	v_mov_b32_e32 v108, v96
	v_mov_b32_e32 v109, v96
	v_mov_b32_e32 v110, v96
	v_mov_b32_e32 v111, v96
